# weight-conversion loops: 16 gain loads per item issued together with one wait instead of 16 serialized load+wait round trips
# speedup vs baseline: 1.0059x; 1.0059x over previous
; #define LAS __attribute__((address_space(3)))
; template <int MODE  >
; __device__ __forceinline__ void p0_transpose_item(const float* W, int K, int N, const float* gain, bf16_t* WT, LAS float* scr, int item, int lane) {
;     const int nblk = N / 64, kb = item / nblk, nb = item % nblk, k0 = 64 * kb, n0 = 64 * nb;
;     const __amdgpu_buffer_rsrc_t wrs = __builtin_amdgcn_make_buffer_rsrc(WT, 0, N * K * 2, 0x00020000);
;     const int lr = lane >> 4, lc = 4 * (lane & 15);
;     f32x4 v[16];
; #pragma unroll
;     for (int i = 0; i < 16; ++i) v[i] = __builtin_nontemporal_load((const f32x4*)(W + (size_t)(k0 + 4 * i + lr) * N + n0 + lc));
; #pragma unroll
;     for (int i = 0; i < 16; ++i) { const int kk = 4 * i + lr; f32x4 x = v[i]; if (gain) x = x * gain[k0 + kk];
;         LAS float* s = scr + kk * 65 + lc; s[0] = x[0]; s[1] = x[1]; s[2] = x[2]; s[3] = x[3]; }
.LBB0_315:
	s_or_saveexec_b64 s[10:11], s[38:39]
	s_mov_b32 s42, s18
	s_xor_b64 exec, exec, s[10:11]
	s_cbranch_execz .LBB0_341
	v_add_u32_e32 v0, 0xfe80, v103
	v_and_b32_e32 v105, 0xffc0, v0
	v_and_b32_e32 v104, 0xfc0, v99
	v_or_b32_e32 v64, v105, v68
	v_lshlrev_b32_e32 v200, 2, v104
	v_lshl_add_u64 v[0:1], v[76:77], 0, v[200:201]
	v_lshlrev_b32_e32 v200, 14, v64
	v_lshl_add_u64 v[0:1], v[0:1], 0, v[200:201]
	v_add_co_u32_e32 v2, vcc, 0x10000, v0
	v_readlane_b32 s12, v254, 35
	s_nop 0
	v_addc_co_u32_e32 v3, vcc, 0, v1, vcc
	global_load_dwordx4 v[56:59], v[0:1], off nt
	global_load_dwordx4 v[60:63], v[2:3], off nt
	v_add_co_u32_e32 v2, vcc, s95, v0
	v_readlane_b32 s13, v254, 36
	s_nop 0
	v_addc_co_u32_e32 v3, vcc, 0, v1, vcc
	v_add_co_u32_e32 v4, vcc, 0x30000, v0
	v_cndmask_b32_e64 v65, 0, 1, s[12:13]
	s_nop 0
	v_addc_co_u32_e32 v5, vcc, 0, v1, vcc
	global_load_dwordx4 v[48:51], v[2:3], off nt
	global_load_dwordx4 v[52:55], v[4:5], off nt
	v_add_co_u32_e32 v2, vcc, 0x40000, v0
	v_cmp_ne_u32_e64 s[38:39], 1, v65
	s_nop 0
	v_addc_co_u32_e32 v3, vcc, 0, v1, vcc
	v_add_co_u32_e32 v4, vcc, 0x50000, v0
	v_add_lshl_u32 v106, v105, v68, 2
	s_nop 0
	v_addc_co_u32_e32 v5, vcc, 0, v1, vcc
	global_load_dwordx4 v[40:43], v[2:3], off nt
	global_load_dwordx4 v[44:47], v[4:5], off nt
	v_add_co_u32_e32 v2, vcc, 0x60000, v0
	s_nop 1
	v_addc_co_u32_e32 v3, vcc, 0, v1, vcc
	v_add_co_u32_e32 v4, vcc, 0x70000, v0
	s_nop 1
	v_addc_co_u32_e32 v5, vcc, 0, v1, vcc
	global_load_dwordx4 v[32:35], v[2:3], off nt
	global_load_dwordx4 v[36:39], v[4:5], off nt
	v_add_co_u32_e32 v2, vcc, 0x80000, v0
	s_nop 1
	v_addc_co_u32_e32 v3, vcc, 0, v1, vcc
	v_add_co_u32_e32 v4, vcc, 0x90000, v0
	s_nop 1
	v_addc_co_u32_e32 v5, vcc, 0, v1, vcc
	global_load_dwordx4 v[24:27], v[2:3], off nt
	global_load_dwordx4 v[28:31], v[4:5], off nt
	v_add_co_u32_e32 v2, vcc, 0xa0000, v0
	s_nop 1
	v_addc_co_u32_e32 v3, vcc, 0, v1, vcc
	v_add_co_u32_e32 v4, vcc, 0xb0000, v0
	s_nop 1
	v_addc_co_u32_e32 v5, vcc, 0, v1, vcc
	global_load_dwordx4 v[16:19], v[2:3], off nt
	global_load_dwordx4 v[20:23], v[4:5], off nt
	v_add_co_u32_e32 v2, vcc, 0xc0000, v0
	s_nop 1
	v_addc_co_u32_e32 v3, vcc, 0, v1, vcc
	v_add_co_u32_e32 v4, vcc, 0xd0000, v0
	s_nop 1
	v_addc_co_u32_e32 v5, vcc, 0, v1, vcc
	global_load_dwordx4 v[8:11], v[2:3], off nt
	global_load_dwordx4 v[12:15], v[4:5], off nt
	v_add_co_u32_e32 v2, vcc, 0xe0000, v0
	s_nop 1
	v_addc_co_u32_e32 v3, vcc, 0, v1, vcc
	v_add_co_u32_e32 v4, vcc, 0xf0000, v0
	s_nop 1
	v_addc_co_u32_e32 v5, vcc, 0, v1, vcc
	global_load_dwordx4 v[0:3], v[2:3], off nt
	s_nop 0
	global_load_dwordx4 v[4:7], v[4:5], off nt
	s_andn2_b64 vcc, exec, s[12:13]
	s_cbranch_vccnz .LBB0_347
	v_lshlrev_b32_e32 v64, 2, v64
	global_load_dword v64, v64, s[24:25]
	s_nop 0
	global_load_dword v108, v106, s[24:25] offset:16
	global_load_dword v112, v106, s[24:25] offset:32
	global_load_dword v113, v106, s[24:25] offset:48
	global_load_dword v114, v106, s[24:25] offset:64
	global_load_dword v115, v106, s[24:25] offset:80
	global_load_dword v116, v106, s[24:25] offset:96
	global_load_dword v117, v106, s[24:25] offset:112
	global_load_dword v118, v106, s[24:25] offset:128
	global_load_dword v119, v106, s[24:25] offset:144
	global_load_dword v120, v106, s[24:25] offset:160
	global_load_dword v121, v106, s[24:25] offset:176
	global_load_dword v122, v106, s[24:25] offset:192
	global_load_dword v123, v106, s[24:25] offset:208
	global_load_dword v124, v106, s[24:25] offset:224
	global_load_dword v125, v106, s[24:25] offset:240
	s_waitcnt vmcnt(0)
	v_pk_mul_f32 v[82:83], v[58:59], v[64:65] op_sel_hi:[1,0]
	v_pk_mul_f32 v[84:85], v[56:57], v[64:65] op_sel_hi:[1,0]
	v_pk_mul_f32 v[66:67], v[62:63], v[108:109] op_sel_hi:[1,0]
	v_pk_mul_f32 v[64:65], v[60:61], v[108:109] op_sel_hi:[1,0]
	s_cbranch_execnz .LBB0_319

; #define LAS __attribute__((address_space(3)))
; template <int MODE  >
; __device__ __forceinline__ void p0_transpose_item(const float* W, int K, int N, const float* gain, bf16_t* WT, LAS float* scr, int item, int lane) {
;     ...
;     for (int i = 0; i < 16; ++i) { const int kk = 4 * i + lr; f32x4 x = v[i]; if (gain) x = x * gain[k0 + kk];
;         LAS float* s = scr + kk * 65 + lc; s[0] = x[0]; s[1] = x[1]; s[2] = x[2]; s[3] = x[3]; }
.LBB0_319:
	s_waitcnt vmcnt(0)
	v_add_u32_e32 v56, v71, v88
	s_and_b64 vcc, exec, s[38:39]
	ds_write2_b32 v86, v84, v85 offset1:1
	ds_write2_b32 v86, v82, v83 offset0:2 offset1:3
	ds_write2_b32 v56, v64, v65 offset1:1
	ds_write2_b32 v56, v66, v67 offset0:2 offset1:3
	s_cbranch_vccnz .LBB0_348
	v_mov_b32_e32 v56, v112
	v_mov_b32_e32 v64, v113
	v_pk_mul_f32 v[60:61], v[50:51], v[56:57] op_sel_hi:[1,0]
	v_pk_mul_f32 v[62:63], v[48:49], v[56:57] op_sel_hi:[1,0]
	v_pk_mul_f32 v[58:59], v[54:55], v[64:65] op_sel_hi:[1,0]
	v_pk_mul_f32 v[56:57], v[52:53], v[64:65] op_sel_hi:[1,0]
	s_cbranch_execnz .LBB0_322

; #define LAS __attribute__((address_space(3)))
; template <int MODE  >
; __device__ __forceinline__ void p0_transpose_item(const float* W, int K, int N, const float* gain, bf16_t* WT, LAS float* scr, int item, int lane) {
;     ...
;     for (int i = 0; i < 16; ++i) { const int kk = 4 * i + lr; f32x4 x = v[i]; if (gain) x = x * gain[k0 + kk];
;         LAS float* s = scr + kk * 65 + lc; s[0] = x[0]; s[1] = x[1]; s[2] = x[2]; s[3] = x[3]; }
.LBB0_322:
	v_add_u32_e32 v48, 0x410, v101
	ds_write2_b32 v101, v62, v63 offset1:1
	ds_write2_b32 v101, v60, v61 offset0:2 offset1:3
	ds_write2_b32 v48, v56, v57 offset1:1
	v_add_u32_e32 v48, 0x418, v101
	s_and_b64 vcc, exec, s[38:39]
	ds_write2_b32 v48, v58, v59 offset1:1
	s_cbranch_vccnz .LBB0_349
	v_mov_b32_e32 v48, v114
	v_mov_b32_e32 v56, v115
	v_pk_mul_f32 v[52:53], v[42:43], v[48:49] op_sel_hi:[1,0]
	v_pk_mul_f32 v[54:55], v[40:41], v[48:49] op_sel_hi:[1,0]
	v_pk_mul_f32 v[50:51], v[46:47], v[56:57] op_sel_hi:[1,0]
	v_pk_mul_f32 v[48:49], v[44:45], v[56:57] op_sel_hi:[1,0]
	s_cbranch_execnz .LBB0_325

; #define LAS __attribute__((address_space(3)))
; template <int MODE  >
; __device__ __forceinline__ void p0_transpose_item(const float* W, int K, int N, const float* gain, bf16_t* WT, LAS float* scr, int item, int lane) {
;     ...
;     for (int i = 0; i < 16; ++i) { const int kk = 4 * i + lr; f32x4 x = v[i]; if (gain) x = x * gain[k0 + kk];
;         LAS float* s = scr + kk * 65 + lc; s[0] = x[0]; s[1] = x[1]; s[2] = x[2]; s[3] = x[3]; }
.LBB0_325:
	v_add_u32_e32 v40, 0x410, v102
	ds_write2_b32 v102, v54, v55 offset1:1
	ds_write2_b32 v102, v52, v53 offset0:2 offset1:3
	ds_write2_b32 v40, v48, v49 offset1:1
	v_add_u32_e32 v40, 0x418, v102
	s_and_b64 vcc, exec, s[38:39]
	ds_write2_b32 v40, v50, v51 offset1:1
	s_cbranch_vccnz .LBB0_350
	v_mov_b32_e32 v40, v116
	v_mov_b32_e32 v48, v117
	v_pk_mul_f32 v[44:45], v[34:35], v[40:41] op_sel_hi:[1,0]
	v_pk_mul_f32 v[46:47], v[32:33], v[40:41] op_sel_hi:[1,0]
	v_pk_mul_f32 v[42:43], v[38:39], v[48:49] op_sel_hi:[1,0]
	v_pk_mul_f32 v[40:41], v[36:37], v[48:49] op_sel_hi:[1,0]
	s_cbranch_execnz .LBB0_328

; #define LAS __attribute__((address_space(3)))
; template <int MODE  >
; __device__ __forceinline__ void p0_transpose_item(const float* W, int K, int N, const float* gain, bf16_t* WT, LAS float* scr, int item, int lane) {
;     ...
;     for (int i = 0; i < 16; ++i) { const int kk = 4 * i + lr; f32x4 x = v[i]; if (gain) x = x * gain[k0 + kk];
;         LAS float* s = scr + kk * 65 + lc; s[0] = x[0]; s[1] = x[1]; s[2] = x[2]; s[3] = x[3]; }
.LBB0_328:
	v_add_u32_e32 v48, v71, v89
	v_add_u32_e32 v32, 0x410, v48
	ds_write2_b32 v48, v46, v47 offset1:1
	ds_write2_b32 v48, v44, v45 offset0:2 offset1:3
	ds_write2_b32 v32, v40, v41 offset1:1
	v_add_u32_e32 v32, 0x418, v48
	s_and_b64 vcc, exec, s[38:39]
	ds_write2_b32 v32, v42, v43 offset1:1
	s_cbranch_vccnz .LBB0_351
	v_mov_b32_e32 v32, v118
	v_mov_b32_e32 v40, v119
	v_pk_mul_f32 v[36:37], v[26:27], v[32:33] op_sel_hi:[1,0]
	v_pk_mul_f32 v[38:39], v[24:25], v[32:33] op_sel_hi:[1,0]
	v_pk_mul_f32 v[34:35], v[30:31], v[40:41] op_sel_hi:[1,0]
	v_pk_mul_f32 v[32:33], v[28:29], v[40:41] op_sel_hi:[1,0]
	s_cbranch_execnz .LBB0_331

; #define LAS __attribute__((address_space(3)))
; template <int MODE  >
; __device__ __forceinline__ void p0_transpose_item(const float* W, int K, int N, const float* gain, bf16_t* WT, LAS float* scr, int item, int lane) {
;     ...
;     for (int i = 0; i < 16; ++i) { const int kk = 4 * i + lr; f32x4 x = v[i]; if (gain) x = x * gain[k0 + kk];
;         LAS float* s = scr + kk * 65 + lc; s[0] = x[0]; s[1] = x[1]; s[2] = x[2]; s[3] = x[3]; }
.LBB0_331:
	v_add_u32_e32 v24, 0x820, v48
	ds_write2_b32 v24, v38, v39 offset1:1
	v_add_u32_e32 v24, 0x828, v48
	ds_write2_b32 v24, v36, v37 offset1:1
	v_add_u32_e32 v24, 0xc30, v48
	ds_write2_b32 v24, v32, v33 offset1:1
	v_add_u32_e32 v24, 0xc38, v48
	s_and_b64 vcc, exec, s[38:39]
	ds_write2_b32 v24, v34, v35 offset1:1
	s_cbranch_vccnz .LBB0_352
	v_mov_b32_e32 v24, v120
	v_mov_b32_e32 v32, v121
	v_pk_mul_f32 v[28:29], v[18:19], v[24:25] op_sel_hi:[1,0]
	v_pk_mul_f32 v[30:31], v[16:17], v[24:25] op_sel_hi:[1,0]
	v_pk_mul_f32 v[26:27], v[22:23], v[32:33] op_sel_hi:[1,0]
	v_pk_mul_f32 v[24:25], v[20:21], v[32:33] op_sel_hi:[1,0]
	s_cbranch_execnz .LBB0_334

; #define LAS __attribute__((address_space(3)))
; template <int MODE  >
; __device__ __forceinline__ void p0_transpose_item(const float* W, int K, int N, const float* gain, bf16_t* WT, LAS float* scr, int item, int lane) {
;     ...
;     for (int i = 0; i < 16; ++i) { const int kk = 4 * i + lr; f32x4 x = v[i]; if (gain) x = x * gain[k0 + kk];
;         LAS float* s = scr + kk * 65 + lc; s[0] = x[0]; s[1] = x[1]; s[2] = x[2]; s[3] = x[3]; }
.LBB0_334:
	v_add_u32_e32 v16, 0x1040, v48
	ds_write2_b32 v16, v30, v31 offset1:1
	v_add_u32_e32 v16, 0x1048, v48
	ds_write2_b32 v16, v28, v29 offset1:1
	v_add_u32_e32 v16, 0x1450, v48
	ds_write2_b32 v16, v24, v25 offset1:1
	v_add_u32_e32 v16, 0x1458, v48
	s_and_b64 vcc, exec, s[38:39]
	ds_write2_b32 v16, v26, v27 offset1:1
	s_cbranch_vccnz .LBB0_353
	v_mov_b32_e32 v16, v122
	v_mov_b32_e32 v24, v123
	v_pk_mul_f32 v[20:21], v[10:11], v[16:17] op_sel_hi:[1,0]
	v_pk_mul_f32 v[22:23], v[8:9], v[16:17] op_sel_hi:[1,0]
	v_pk_mul_f32 v[18:19], v[14:15], v[24:25] op_sel_hi:[1,0]
	v_pk_mul_f32 v[16:17], v[12:13], v[24:25] op_sel_hi:[1,0]
	s_cbranch_execnz .LBB0_337

; #define LAS __attribute__((address_space(3)))
; template <int MODE  >
; __device__ __forceinline__ void p0_transpose_item(const float* W, int K, int N, const float* gain, bf16_t* WT, LAS float* scr, int item, int lane) {
;     ...
;     for (int i = 0; i < 16; ++i) { const int kk = 4 * i + lr; f32x4 x = v[i]; if (gain) x = x * gain[k0 + kk];
;         LAS float* s = scr + kk * 65 + lc; s[0] = x[0]; s[1] = x[1]; s[2] = x[2]; s[3] = x[3]; }
.LBB0_337:
	v_add_u32_e32 v8, 0x1860, v48
	ds_write2_b32 v8, v22, v23 offset1:1
	v_add_u32_e32 v8, 0x1868, v48
	ds_write2_b32 v8, v20, v21 offset1:1
	v_add_u32_e32 v8, 0x1c70, v48
	ds_write2_b32 v8, v16, v17 offset1:1
	v_add_u32_e32 v8, 0x1c78, v48
	s_and_b64 vcc, exec, s[38:39]
	ds_write2_b32 v8, v18, v19 offset1:1
	s_cbranch_vccnz .LBB0_354
	v_mov_b32_e32 v8, v124
	v_mov_b32_e32 v16, v125
	v_pk_mul_f32 v[12:13], v[2:3], v[8:9] op_sel_hi:[1,0]
	v_pk_mul_f32 v[14:15], v[0:1], v[8:9] op_sel_hi:[1,0]
	v_pk_mul_f32 v[10:11], v[6:7], v[16:17] op_sel_hi:[1,0]
	v_pk_mul_f32 v[8:9], v[4:5], v[16:17] op_sel_hi:[1,0]
	s_cbranch_execnz .LBB0_340

; #define LAS __attribute__((address_space(3)))
; template <int MODE  >
; __device__ __forceinline__ void p0_transpose_item(const float* W, int K, int N, const float* gain, bf16_t* WT, LAS float* scr, int item, int lane) {
;     const int nblk = N / 64, kb = item / nblk, nb = item % nblk, k0 = 64 * kb, n0 = 64 * nb;
;     const __amdgpu_buffer_rsrc_t wrs = __builtin_amdgcn_make_buffer_rsrc(WT, 0, N * K * 2, 0x00020000);
;     const int lr = lane >> 4, lc = 4 * (lane & 15);
;     f32x4 v[16];
; #pragma unroll
;     for (int i = 0; i < 16; ++i) v[i] = __builtin_nontemporal_load((const f32x4*)(W + (size_t)(k0 + 4 * i + lr) * N + n0 + lc));
; #pragma unroll
;     for (int i = 0; i < 16; ++i) { const int kk = 4 * i + lr; f32x4 x = v[i]; if (gain) x = x * gain[k0 + kk];
;         LAS float* s = scr + kk * 65 + lc; s[0] = x[0]; s[1] = x[1]; s[2] = x[2]; s[3] = x[3]; }
.LBB0_357:
	s_mov_b32 s8, 0x66666667
	v_mul_hi_i32 v0, v69, s8
	v_lshrrev_b32_e32 v1, 31, v0
	v_ashrrev_i32_e32 v0, 3, v0
	v_add_u32_e32 v59, v0, v1
	s_movk_i32 s8, 0xfb00
	v_mad_u64_u32 v[0:1], s[8:9], v59, s8, v[70:71]
	v_lshlrev_b32_e32 v74, 6, v59
	v_ashrrev_i32_e32 v1, 31, v0
	v_or_b32_e32 v72, v74, v68
	v_lshl_add_u64 v[0:1], v[0:1], 2, v[56:57]
	v_mad_i64_i32 v[2:3], s[8:9], v72, s61, v[0:1]
	global_load_dwordx4 v[60:63], v[2:3], off nt
	v_or_b32_e32 v2, 4, v72
	v_mad_i64_i32 v[2:3], s[8:9], v2, s61, v[0:1]
	global_load_dwordx4 v[64:67], v[2:3], off nt
	v_or_b32_e32 v2, 8, v72
	v_mad_i64_i32 v[2:3], s[8:9], v2, s61, v[0:1]
	global_load_dwordx4 v[52:55], v[2:3], off nt
	v_or_b32_e32 v2, 12, v72
	v_mad_i64_i32 v[2:3], s[8:9], v2, s61, v[0:1]
	global_load_dwordx4 v[48:51], v[2:3], off nt
	v_or_b32_e32 v2, 16, v72
	v_mad_i64_i32 v[2:3], s[8:9], v2, s61, v[0:1]
	global_load_dwordx4 v[44:47], v[2:3], off nt
	v_or_b32_e32 v2, 20, v72
	v_mad_i64_i32 v[2:3], s[8:9], v2, s61, v[0:1]
	global_load_dwordx4 v[40:43], v[2:3], off nt
	v_or_b32_e32 v2, 24, v72
	v_mad_i64_i32 v[2:3], s[8:9], v2, s61, v[0:1]
	global_load_dwordx4 v[36:39], v[2:3], off nt
	v_or_b32_e32 v2, 28, v72
	v_mad_i64_i32 v[2:3], s[8:9], v2, s61, v[0:1]
	global_load_dwordx4 v[32:35], v[2:3], off nt
	v_or_b32_e32 v2, 32, v72
	v_mad_i64_i32 v[2:3], s[8:9], v2, s61, v[0:1]
	global_load_dwordx4 v[28:31], v[2:3], off nt
	v_or_b32_e32 v2, 36, v72
	v_mad_i64_i32 v[2:3], s[8:9], v2, s61, v[0:1]
	global_load_dwordx4 v[24:27], v[2:3], off nt
	v_or_b32_e32 v2, 40, v72
	v_mad_i64_i32 v[2:3], s[8:9], v2, s61, v[0:1]
	global_load_dwordx4 v[20:23], v[2:3], off nt
	v_or_b32_e32 v2, 44, v72
	v_mad_i64_i32 v[2:3], s[8:9], v2, s61, v[0:1]
	global_load_dwordx4 v[16:19], v[2:3], off nt
	v_or_b32_e32 v2, 48, v72
	v_mad_i64_i32 v[2:3], s[8:9], v2, s61, v[0:1]
	global_load_dwordx4 v[12:15], v[2:3], off nt
	v_or_b32_e32 v2, 52, v72
	v_mad_i64_i32 v[2:3], s[8:9], v2, s61, v[0:1]
	global_load_dwordx4 v[8:11], v[2:3], off nt
	v_or_b32_e32 v2, 56, v72
	v_ashrrev_i32_e32 v73, 31, v72
	v_mad_i64_i32 v[2:3], s[8:9], v2, s61, v[0:1]
	global_load_dwordx4 v[4:7], v[2:3], off nt
	v_or_b32_e32 v2, 60, v72
	v_lshl_add_u64 v[72:73], v[72:73], 2, s[16:17]
	global_load_dword v110, v[72:73], off
	global_load_dword v111, v[72:73], off offset:16
	global_load_dword v112, v[72:73], off offset:32
	global_load_dword v113, v[72:73], off offset:48
	global_load_dword v114, v[72:73], off offset:64
	global_load_dword v115, v[72:73], off offset:80
	global_load_dword v116, v[72:73], off offset:96
	global_load_dword v117, v[72:73], off offset:112
	global_load_dword v118, v[72:73], off offset:128
	global_load_dword v119, v[72:73], off offset:144
	global_load_dword v120, v[72:73], off offset:160
	global_load_dword v121, v[72:73], off offset:176
	global_load_dword v122, v[72:73], off offset:192
	global_load_dword v123, v[72:73], off offset:208
	global_load_dword v124, v[72:73], off offset:224
	global_load_dword v125, v[72:73], off offset:240
	v_mad_i64_i32 v[0:1], s[8:9], v2, s61, v[0:1]
	global_load_dwordx4 v[0:3], v[0:1], off nt
	s_mov_b32 s8, 0xffd80080
	v_add_u32_e32 v69, s37, v69
	v_add_u32_e32 v70, s7, v70
	s_waitcnt vmcnt(0)
	v_mov_b32_e32 v72, v110
	v_pk_mul_f32 v[60:61], v[60:61], v[72:73] op_sel_hi:[1,0]
	v_pk_mul_f32 v[62:63], v[62:63], v[72:73] op_sel_hi:[1,0]
	ds_write2_b32 v86, v60, v61 offset1:1
	ds_write2_b32 v86, v62, v63 offset0:2 offset1:3
	v_ashrrev_i32_e32 v61, 31, v74
	v_or_b32_e32 v60, v74, v68
	v_lshl_add_u64 v[60:61], v[60:61], 2, s[16:17]
	v_mov_b32_e32 v72, v111
	v_pk_mul_f32 v[62:63], v[66:67], v[72:73] op_sel_hi:[1,0]
	v_pk_mul_f32 v[64:65], v[64:65], v[72:73] op_sel_hi:[1,0]
	v_add_u32_e32 v66, v71, v88
	ds_write2_b32 v66, v64, v65 offset1:1
	ds_write2_b32 v66, v62, v63 offset0:2 offset1:3
	v_mov_b32_e32 v62, v112
	v_pk_mul_f32 v[54:55], v[54:55], v[62:63] op_sel_hi:[1,0]
	v_pk_mul_f32 v[52:53], v[52:53], v[62:63] op_sel_hi:[1,0]
	v_add_u32_e32 v62, 0x410, v66
	ds_write2_b32 v62, v52, v53 offset1:1
	v_add_u32_e32 v52, 0x418, v66
	ds_write2_b32 v52, v54, v55 offset1:1
	v_mov_b32_e32 v52, v113
	v_pk_mul_f32 v[50:51], v[50:51], v[52:53] op_sel_hi:[1,0]
	v_pk_mul_f32 v[48:49], v[48:49], v[52:53] op_sel_hi:[1,0]
	v_add_u32_e32 v52, 0x820, v66
	ds_write2_b32 v52, v48, v49 offset1:1
	v_add_u32_e32 v48, 0x828, v66
	ds_write2_b32 v48, v50, v51 offset1:1
	v_mov_b32_e32 v48, v114
	v_pk_mul_f32 v[46:47], v[46:47], v[48:49] op_sel_hi:[1,0]
	v_pk_mul_f32 v[44:45], v[44:45], v[48:49] op_sel_hi:[1,0]
	v_add_u32_e32 v48, 0xc30, v66
	ds_write2_b32 v48, v44, v45 offset1:1
	v_add_u32_e32 v44, 0xc38, v66
	ds_write2_b32 v44, v46, v47 offset1:1
	v_mov_b32_e32 v44, v115
	v_pk_mul_f32 v[42:43], v[42:43], v[44:45] op_sel_hi:[1,0]
	v_pk_mul_f32 v[40:41], v[40:41], v[44:45] op_sel_hi:[1,0]
	v_add_u32_e32 v44, 0x1040, v66
	ds_write2_b32 v44, v40, v41 offset1:1
	v_add_u32_e32 v40, 0x1048, v66
	ds_write2_b32 v40, v42, v43 offset1:1
	v_mov_b32_e32 v40, v116
	v_pk_mul_f32 v[38:39], v[38:39], v[40:41] op_sel_hi:[1,0]
	v_pk_mul_f32 v[36:37], v[36:37], v[40:41] op_sel_hi:[1,0]
	v_add_u32_e32 v40, 0x1450, v66
	ds_write2_b32 v40, v36, v37 offset1:1
	v_mov_b32_e32 v36, v117
	v_add_u32_e32 v37, v71, v89
	ds_write2_b32 v37, v38, v39 offset0:2 offset1:3
	v_pk_mul_f32 v[34:35], v[34:35], v[36:37] op_sel_hi:[1,0]
	v_pk_mul_f32 v[32:33], v[32:33], v[36:37] op_sel_hi:[1,0]
	v_add_u32_e32 v36, 0x410, v37
	ds_write2_b32 v36, v32, v33 offset1:1
	v_add_u32_e32 v32, 0x418, v37
	ds_write2_b32 v32, v34, v35 offset1:1
	v_mov_b32_e32 v32, v118
	v_pk_mul_f32 v[30:31], v[30:31], v[32:33] op_sel_hi:[1,0]
	v_pk_mul_f32 v[28:29], v[28:29], v[32:33] op_sel_hi:[1,0]
; #define LAS __attribute__((address_space(3)))
; __device__ __forceinline__ unsigned pk2(float lo, float hi) { f32x2 v = {lo, hi}; bf2_t b = __builtin_convertvector(v, bf2_t); return __builtin_bit_cast(unsigned, b); }
; template <int MODE  >
; __device__ __forceinline__ void p0_transpose_item(const float* W, int K, int N, const float* gain, bf16_t* WT, LAS float* scr, int item, int lane) {
;     ...
;     for (int i = 0; i < 16; ++i) { const int kk = 4 * i + lr; f32x4 x = v[i]; if (gain) x = x * gain[k0 + kk];
;         LAS float* s = scr + kk * 65 + lc; s[0] = x[0]; s[1] = x[1]; s[2] = x[2]; s[3] = x[3]; }
;     asm volatile("s_waitcnt lgkmcnt(0)" ::: "memory");
; #pragma unroll
;     for (int j = 0; j < 8; ++j) { const int piece = lane + 64 * j, n = piece >> 3, c = piece & 7; const LAS float* s = scr + (8 * c) * 65 + n;
;         u32x4 o; o.x = pk2(s[0 * 65], s[1 * 65]); o.y = pk2(s[2 * 65], s[3 * 65]); o.z = pk2(s[4 * 65], s[5 * 65]); o.w = pk2(s[6 * 65], s[7 * 65]);
;         const int nn = n0 + n; const int orow = (MODE == 1) ? (nn < 512 ? 2 * nn : 2 * (nn - 512) + 1) : nn;
;         __builtin_amdgcn_raw_buffer_store_b128(o, wrs, (unsigned)((orow * K + k0 + 8 * c) * 2), 0,   16); }
;     asm volatile("s_waitcnt lgkmcnt(0)" ::: "memory");
	v_add_u32_e32 v32, 0x820, v37
	ds_write2_b32 v32, v28, v29 offset1:1
	v_add_u32_e32 v28, 0x828, v37
	ds_write2_b32 v28, v30, v31 offset1:1
	v_mov_b32_e32 v28, v119
	v_pk_mul_f32 v[26:27], v[26:27], v[28:29] op_sel_hi:[1,0]
	v_pk_mul_f32 v[24:25], v[24:25], v[28:29] op_sel_hi:[1,0]
	v_add_u32_e32 v28, 0xc30, v37
	ds_write2_b32 v28, v24, v25 offset1:1
	v_add_u32_e32 v24, 0xc38, v37
	ds_write2_b32 v24, v26, v27 offset1:1
	v_mov_b32_e32 v24, v120
	v_pk_mul_f32 v[22:23], v[22:23], v[24:25] op_sel_hi:[1,0]
	v_pk_mul_f32 v[20:21], v[20:21], v[24:25] op_sel_hi:[1,0]
	v_add_u32_e32 v24, 0x1040, v37
	ds_write2_b32 v24, v20, v21 offset1:1
	v_add_u32_e32 v20, 0x1048, v37
	ds_write2_b32 v20, v22, v23 offset1:1
	v_mov_b32_e32 v20, v121
	v_add_u32_e32 v22, 0x400, v87
	v_pk_mul_f32 v[18:19], v[18:19], v[20:21] op_sel_hi:[1,0]
	v_pk_mul_f32 v[16:17], v[16:17], v[20:21] op_sel_hi:[1,0]
	v_add_u32_e32 v20, 0x1450, v37
	ds_write2_b32 v20, v16, v17 offset1:1
	v_add_u32_e32 v16, 0x1458, v37
	ds_write2_b32 v16, v18, v19 offset1:1
	v_mov_b32_e32 v16, v122
	v_mad_u64_u32 v[20:21], s[8:9], v59, s8, v[58:59]
	s_movk_i32 s8, 0x13f
	s_nop 0
	v_cmp_lt_i32_e32 vcc, s8, v69
	v_add_u32_e32 v58, s5, v58
	s_or_b64 s[20:21], vcc, s[20:21]
	v_pk_mul_f32 v[14:15], v[14:15], v[16:17] op_sel_hi:[1,0]
	v_pk_mul_f32 v[12:13], v[12:13], v[16:17] op_sel_hi:[1,0]
	v_add_u32_e32 v16, 0x1860, v37
	ds_write2_b32 v16, v12, v13 offset1:1
	v_add_u32_e32 v12, 0x1868, v37
	ds_write2_b32 v12, v14, v15 offset1:1
	v_mov_b32_e32 v12, v123
	v_pk_mul_f32 v[10:11], v[10:11], v[12:13] op_sel_hi:[1,0]
	v_pk_mul_f32 v[8:9], v[8:9], v[12:13] op_sel_hi:[1,0]
	v_add_u32_e32 v12, 0x1c70, v37
	ds_write2_b32 v12, v8, v9 offset1:1
	v_add_u32_e32 v8, 0x1c78, v37
	ds_write2_b32 v8, v10, v11 offset1:1
	v_mov_b32_e32 v8, v124
	v_pk_mul_f32 v[6:7], v[6:7], v[8:9] op_sel_hi:[1,0]
	v_pk_mul_f32 v[4:5], v[4:5], v[8:9] op_sel_hi:[1,0]
	v_add_u32_e32 v8, 0x2080, v37
	ds_write2_b32 v8, v4, v5 offset1:1
	v_add_u32_e32 v4, 0x2088, v37
	ds_write2_b32 v4, v6, v7 offset1:1
	v_mov_b32_e32 v4, v125
	v_pk_mul_f32 v[2:3], v[2:3], v[4:5] op_sel_hi:[1,0]
	v_pk_mul_f32 v[0:1], v[0:1], v[4:5] op_sel_hi:[1,0]
	v_add_u32_e32 v4, 0x2490, v37
	ds_write2_b32 v4, v0, v1 offset1:1
	v_add_u32_e32 v0, 0x2498, v37
	ds_write2_b32 v0, v2, v3 offset1:1
	s_waitcnt lgkmcnt(0)
	ds_read2_b32 v[4:5], v87 offset1:8
	ds_read2_b32 v[6:7], v87 offset0:65 offset1:73
	ds_read2_b32 v[8:9], v87 offset0:130 offset1:138
	ds_read2_b32 v[10:11], v87 offset0:195 offset1:203
	ds_read2_b32 v[12:13], v22 offset0:4 offset1:12
	ds_read2_b32 v[14:15], v22 offset0:69 offset1:77
	ds_read2_b32 v[16:17], v22 offset0:134 offset1:142
	ds_read2_b32 v[18:19], v22 offset0:199 offset1:207
	s_waitcnt lgkmcnt(0)
	v_cvt_pk_bf16_f32 v0, v4, v6
	v_cvt_pk_bf16_f32 v1, v8, v10
	v_cvt_pk_bf16_f32 v2, v12, v14
	v_cvt_pk_bf16_f32 v3, v16, v18
	v_add_u32_e32 v4, 0xfffe4000, v20
	buffer_store_dwordx4 v[0:3], v4, s[12:15], 0 offen sc1
	v_add_u32_e32 v4, 0xfffe8000, v20
	s_nop 0
	v_cvt_pk_bf16_f32 v0, v5, v7
	v_cvt_pk_bf16_f32 v1, v9, v11
	v_cvt_pk_bf16_f32 v2, v13, v15
	v_cvt_pk_bf16_f32 v3, v17, v19
	buffer_store_dwordx4 v[0:3], v4, s[12:15], 0 offen sc1
	ds_read2_b32 v[4:5], v87 offset0:16 offset1:24
	ds_read2_b32 v[6:7], v87 offset0:81 offset1:89
	ds_read2_b32 v[8:9], v87 offset0:146 offset1:154
	ds_read2_b32 v[10:11], v87 offset0:211 offset1:219
	ds_read2_b32 v[12:13], v22 offset0:20 offset1:28
	ds_read2_b32 v[14:15], v22 offset0:85 offset1:93
	ds_read2_b32 v[16:17], v22 offset0:150 offset1:158
	ds_read2_b32 v[18:19], v22 offset0:215 offset1:223
	s_waitcnt lgkmcnt(6)
	v_cvt_pk_bf16_f32 v0, v4, v6
	s_waitcnt lgkmcnt(4)
	v_cvt_pk_bf16_f32 v1, v8, v10
	s_waitcnt lgkmcnt(2)
	v_cvt_pk_bf16_f32 v2, v12, v14
	s_waitcnt lgkmcnt(0)
	v_cvt_pk_bf16_f32 v3, v16, v18
	v_add_u32_e32 v4, 0xfffec000, v20
	buffer_store_dwordx4 v[0:3], v4, s[12:15], 0 offen sc1
	v_add_u32_e32 v4, 0xffff0000, v20
	s_nop 0
	v_cvt_pk_bf16_f32 v0, v5, v7
	v_cvt_pk_bf16_f32 v1, v9, v11
	v_cvt_pk_bf16_f32 v2, v13, v15
	v_cvt_pk_bf16_f32 v3, v17, v19
	buffer_store_dwordx4 v[0:3], v4, s[12:15], 0 offen sc1
	ds_read2_b32 v[4:5], v87 offset0:32 offset1:40
	ds_read2_b32 v[6:7], v87 offset0:97 offset1:105
	ds_read2_b32 v[8:9], v87 offset0:162 offset1:170
	ds_read2_b32 v[10:11], v87 offset0:227 offset1:235
	ds_read2_b32 v[12:13], v22 offset0:36 offset1:44
	ds_read2_b32 v[14:15], v22 offset0:101 offset1:109
	ds_read2_b32 v[16:17], v22 offset0:166 offset1:174
	ds_read2_b32 v[18:19], v22 offset0:231 offset1:239
	s_waitcnt lgkmcnt(6)
	v_cvt_pk_bf16_f32 v0, v4, v6
	s_waitcnt lgkmcnt(4)
	v_cvt_pk_bf16_f32 v1, v8, v10
	s_waitcnt lgkmcnt(2)
	v_cvt_pk_bf16_f32 v2, v12, v14
	s_waitcnt lgkmcnt(0)
	v_cvt_pk_bf16_f32 v3, v16, v18
	v_add_u32_e32 v4, 0xffff4000, v20
	buffer_store_dwordx4 v[0:3], v4, s[12:15], 0 offen sc1
	v_add_u32_e32 v4, 0xffff8000, v20
	s_nop 0
	v_cvt_pk_bf16_f32 v0, v5, v7
	v_cvt_pk_bf16_f32 v1, v9, v11
	v_cvt_pk_bf16_f32 v2, v13, v15
	v_cvt_pk_bf16_f32 v3, v17, v19
	buffer_store_dwordx4 v[0:3], v4, s[12:15], 0 offen sc1
	ds_read2_b32 v[4:5], v87 offset0:48 offset1:56
	ds_read2_b32 v[6:7], v87 offset0:113 offset1:121
	ds_read2_b32 v[8:9], v87 offset0:178 offset1:186
	ds_read2_b32 v[10:11], v87 offset0:243 offset1:251
	ds_read2_b32 v[12:13], v22 offset0:52 offset1:60
	ds_read2_b32 v[14:15], v22 offset0:117 offset1:125
	ds_read2_b32 v[16:17], v22 offset0:182 offset1:190
	ds_read2_b32 v[18:19], v22 offset0:247 offset1:255
	s_waitcnt lgkmcnt(6)
	v_cvt_pk_bf16_f32 v0, v4, v6
	s_waitcnt lgkmcnt(4)
	v_cvt_pk_bf16_f32 v1, v8, v10
	s_waitcnt lgkmcnt(2)
	v_cvt_pk_bf16_f32 v2, v12, v14
	s_waitcnt lgkmcnt(0)
	v_cvt_pk_bf16_f32 v3, v16, v18
	v_add_u32_e32 v4, 0xffffc000, v20
	buffer_store_dwordx4 v[0:3], v4, s[12:15], 0 offen sc1
	s_nop 1
	v_cvt_pk_bf16_f32 v0, v5, v7
	v_cvt_pk_bf16_f32 v1, v9, v11
	v_cvt_pk_bf16_f32 v2, v13, v15
	v_cvt_pk_bf16_f32 v3, v17, v19
	buffer_store_dwordx4 v[0:3], v20, s[12:15], 0 offen sc1
	s_waitcnt lgkmcnt(0)
	s_andn2_b64 exec, exec, s[20:21]
	s_cbranch_execnz .LBB0_357
